# pair-GEMM epilogue cache-hit path: no longer drains the next-tile stage loads (vmcnt(0) removed; the K loop's own counted waits cover them)
# speedup vs baseline: 1.0002x; 1.0002x over previous
.Lepc_hit:
	v_lshrrev_b32_e32 v182, 6, v199
	v_and_b32_e32 v183, 15, v199
	v_lshlrev_b32_e32 v182, 9, v182
	v_lshl_add_u32 v183, v183, 2, v182
	v_add_u32_e32 v183, 0x20040, v183
	ds_read_b32 v169, v183
	ds_read_b32 v167, v183 offset:64
	ds_read_b32 v147, v183 offset:128
	ds_read_b32 v145, v183 offset:192
	ds_read_b32 v143, v183 offset:256
	ds_read_b32 v141, v183 offset:320
	ds_read_b32 v139, v183 offset:384
	ds_read_b32 v135, v183 offset:448
	v_lshl_add_u32 v180, s34, 8, v184
	v_or_b32_e32 v178, 16, v180
	v_or_b32_e32 v176, 32, v180
	v_or_b32_e32 v174, 48, v180
	v_add_u32_e32 v172, 0x80, v180
	v_add_u32_e32 v170, 0x90, v180
	v_add_u32_e32 v168, 0xa0, v180
	v_add_u32_e32 v166, 0xb0, v180
	v_readlane_b32 s50, v250, 58
	v_readlane_b32 s51, v250, 59
	v_pk_mul_f32 v[124:125], v[120:121], v[124:125]
	v_pk_mul_f32 v[116:117], v[112:113], v[116:117]
	v_pk_mul_f32 v[108:109], v[104:105], v[108:109]
	v_pk_mul_f32 v[100:101], v[96:97], v[100:101]
	v_pk_mul_f32 v[92:93], v[88:89], v[92:93]
	v_pk_mul_f32 v[84:85], v[80:81], v[84:85]
	v_pk_mul_f32 v[76:77], v[72:73], v[76:77]
	v_pk_mul_f32 v[68:69], v[64:65], v[68:69]
	v_pk_mul_f32 v[60:61], v[56:57], v[60:61]
	v_pk_mul_f32 v[52:53], v[48:49], v[52:53]
	v_pk_mul_f32 v[44:45], v[40:41], v[44:45]
	v_pk_mul_f32 v[36:37], v[32:33], v[36:37]
	v_pk_mul_f32 v[28:29], v[24:25], v[28:29]
	v_pk_mul_f32 v[20:21], v[16:17], v[20:21]
	v_pk_mul_f32 v[12:13], v[8:9], v[12:13]
	v_pk_mul_f32 v[4:5], v[0:1], v[4:5]
	v_lshl_or_b32 v132, s33, 7, v186
	v_ashrrev_i32_e32 v133, 31, v132
	v_lshlrev_b64 v[136:137], 1, v[132:133]
	s_waitcnt lgkmcnt(0)
	v_mul_f32_e32 v150, v169, v169
	v_mul_f32_e32 v148, v167, v167
	v_mul_f32_e32 v146, v147, v147
	v_mul_f32_e32 v144, v145, v145
	v_mul_f32_e32 v142, v143, v143
	v_mul_f32_e32 v140, v141, v141
	v_mul_f32_e32 v138, v139, v139
	s_mov_b64 s[34:35], -1
